# G2 scan units dealt per XCD (batch x>>1 on XCD x): half of each unit's chunk traffic stays in the L2 that G1 wrote and G3 reads
# baseline (speedup 1.0000x reference)
; __device__ __forceinline__ void gla_g2(const Params& P, unsigned char* lds) {
;     const int tid = threadIdx.x; bf16_t* KVT = (bf16_t*)(P.ws + O_KVT); const float* dec = (const float*)(P.ws + O_DEC); float* tile = (float*)lds;
;     const int dvl = tid >> 5, dk4 = (tid & 31) * 4, odk = tid >> 2, odv4 = (tid & 3) * 4;
;     for (int u = blockIdx.x; u < 256; u += gridDim.x) {
;         const int bh = u >> 4, dvb = u & 15, dv = dvb * 16 + dvl; f32x4 S = (f32x4){0.f, 0.f, 0.f, 0.f};
;         for (int cb = 0; cb < 8; ++cb) {
;             u32x2 kv[8]; f32x4 d[8];
; #pragma unroll
;             for (int j = 0; j < 8; ++j) { const int it = bh * 64 + cb * 8 + j; kv[j] = *(const u32x2*)(KVT + ((size_t)it * 256 + dv) * 128 + dk4); d[j] = *(const f32x4*)(dec + (size_t)it * 128 + dk4); }
;     ...
;     for (int u = blockIdx.x; u < 1024; u += gridDim.x) {
;         const int j = u >> 4, dvb = u & 15, it = 1024 + j, dv = dvb * 16 + dvl;
;         __syncthreads();
;         { const f32x4 v = *(const f32x4*)(P.in[3] + ((size_t)j * 128 + odk) * 256 + dvb * 16 + odv4);
; #pragma unroll
;             for (int i = 0; i < 4; ++i) tile[odk * 17 + odv4 + i] = v[i]; }
;         __syncthreads();
;         f32x4 s, f;
; #pragma unroll
;         for (int i = 0; i < 4; ++i) s[i] = tile[(dk4 + i) * 17 + dvl];
;         const u32x2 kv = *(const u32x2*)(KVT + ((size_t)it * 256 + dv) * 128 + dk4); const f32x4 d = *(const f32x4*)(dec + (size_t)it * 128 + dk4);
.LBB0_2073:
	s_cmp_lt_i32 s56, 8
	s_cselect_b64 s[6:7], -1, 0
	s_cmp_gt_i32 s57, 7
	s_cselect_b64 s[8:9], -1, 0
	s_and_b64 s[6:7], s[6:7], s[8:9]
	s_andn2_b64 vcc, exec, s[6:7]
	s_cbranch_vccnz .LBB0_2136
	s_waitcnt vmcnt(0) lgkmcnt(0)
	s_load_dwordx2 s[6:7], s[0:1], 0x18
	v_lshrrev_b32_e32 v20, 5, v210
	v_and_b32_e32 v21, 31, v210
	v_lshlrev_b32_e32 v21, 2, v21
	v_lshrrev_b32_e32 v22, 2, v210
	v_and_b32_e32 v23, 3, v210
	v_lshlrev_b32_e32 v23, 2, v23
	s_and_b32 s9, s2, 7
	s_lshr_b32 s10, s2, 3
	s_and_b32 s8, s9, 1
	s_lshl_b32 s8, s8, 5
	s_add_i32 s10, s10, s8
	s_lshr_b32 s8, s9, 1
	s_lshl_b32 s8, s8, 2
	s_lshr_b32 s9, s10, 4
	s_add_i32 s8, s8, s9
	s_and_b32 s9, s10, 15
	s_lshr_b32 s10, s2, 4
	s_and_b32 s11, s2, 15
	s_cmpk_eq_i32 s58, 0x100
	s_cselect_b32 s8, s8, s10
	s_cselect_b32 s9, s9, s11
	s_lshl_b32 s10, s9, 4
	v_add_u32_e32 v24, s10, v20
	v_lshlrev_b32_e32 v24, 8, v24
	v_lshl_add_u32 v24, v21, 1, v24
	v_lshlrev_b32_e32 v25, 2, v21
	v_mul_u32_u24_e32 v26, 17, v21
	v_add_u32_e32 v26, v26, v20
	v_lshlrev_b32_e32 v26, 2, v26
	v_mul_u32_u24_e32 v27, 17, v22
	v_add_u32_e32 v27, v27, v23
	v_lshlrev_b32_e32 v27, 2, v27
	s_lshl_b32 s10, s9, 6
	v_lshl_add_u32 v28, v22, 8, v23
	v_lshl_add_u32 v28, v28, 2, s10
	s_add_u32 s10, s54, 0xbacdc00
	s_addc_u32 s11, s55, 0
	s_lshl_b32 s12, s8, 22
	s_add_u32 s10, s10, s12
	s_addc_u32 s11, s11, 0
	s_mov_b64 s[12:13], s[10:11]
	s_add_u32 s14, s54, 0x2ffdc00
	s_addc_u32 s15, s55, 0
	s_lshl_b32 s16, s8, 15
	s_add_u32 s14, s14, s16
	s_addc_u32 s15, s15, 0
	s_add_u32 s18, s54, 0xbacdc00
	s_addc_u32 s19, s55, 0
	s_lshl_b32 s16, s8, 16
	s_add_u32 s16, s16, 0x4000000
	s_add_u32 s18, s18, s16
	s_addc_u32 s19, s19, 0
	s_add_u32 s98, s54, 0x2ffdc00
	s_addc_u32 s99, s55, 0
	s_lshl_b32 s16, s8, 9
	s_add_u32 s16, s16, 0x80000
	s_add_u32 s98, s98, s16
	s_addc_u32 s99, s99, 0
	s_lshl_b32 s16, s8, 17
	s_waitcnt lgkmcnt(0)
	s_add_u32 s6, s6, s16
	s_addc_u32 s7, s7, 0
	s_add_u32 s100, s52, 0x442c000
	s_addc_u32 s101, s53, 0
	s_add_u32 s100, s100, s16
	s_addc_u32 s101, s101, 0
	s_add_u32 s16, s52, 0x422c000
	s_addc_u32 s17, s53, 0
	s_lshl_b32 s9, s8, 17
	s_add_u32 s16, s16, s9
	s_addc_u32 s17, s17, 0
	global_load_dwordx4 v[60:63], v28, s[6:7]
	global_load_dwordx2 v[64:65], v24, s[18:19]
	global_load_dwordx4 v[66:69], v25, s[98:99]
	v_add_u32_e32 v44, 0x200000, v28
	global_load_dwordx4 v[70:73], v44, s[6:7]
	v_add_u32_e32 v45, 0x100000, v24
	global_load_dwordx2 v[74:75], v45, s[18:19]
	v_add_u32_e32 v46, 0x2000, v25
	global_load_dwordx4 v[76:79], v46, s[98:99]
	v_add_u32_e32 v44, 0x400000, v28
	global_load_dwordx4 v[80:83], v44, s[6:7]
	v_add_u32_e32 v45, 0x200000, v24
	global_load_dwordx2 v[84:85], v45, s[18:19]
	v_add_u32_e32 v46, 0x4000, v25
	global_load_dwordx4 v[86:89], v46, s[98:99]
	v_add_u32_e32 v44, 0x600000, v28
	global_load_dwordx4 v[90:93], v44, s[6:7]
	v_add_u32_e32 v45, 0x300000, v24
	global_load_dwordx2 v[94:95], v45, s[18:19]
	v_add_u32_e32 v46, 0x6000, v25
	global_load_dwordx4 v[96:99], v46, s[98:99]
	v_mov_b32_e32 v30, 0
	v_mov_b32_e32 v31, 0
	v_mov_b32_e32 v32, 0
	v_mov_b32_e32 v33, 0
	global_load_dwordx2 v[100:101], v24, s[10:11]
	global_load_dwordx4 v[102:105], v25, s[14:15]
	s_add_u32 s10, s10, 0x10000
	s_addc_u32 s11, s11, 0
	s_add_u32 s14, s14, 0x200
	s_addc_u32 s15, s15, 0
	global_load_dwordx2 v[106:107], v24, s[10:11]
	global_load_dwordx4 v[108:111], v25, s[14:15]
	s_add_u32 s10, s10, 0x10000
	s_addc_u32 s11, s11, 0
	s_add_u32 s14, s14, 0x200
	s_addc_u32 s15, s15, 0
	global_load_dwordx2 v[112:113], v24, s[10:11]
	global_load_dwordx4 v[114:117], v25, s[14:15]
	s_add_u32 s10, s10, 0x10000
	s_addc_u32 s11, s11, 0
	s_add_u32 s14, s14, 0x200
	s_addc_u32 s15, s15, 0
	global_load_dwordx2 v[118:119], v24, s[10:11]
	global_load_dwordx4 v[120:123], v25, s[14:15]
	s_add_u32 s10, s10, 0x10000
	s_addc_u32 s11, s11, 0
	s_add_u32 s14, s14, 0x200
	s_addc_u32 s15, s15, 0
	global_load_dwordx2 v[124:125], v24, s[10:11]
	global_load_dwordx4 v[126:129], v25, s[14:15]
	s_add_u32 s10, s10, 0x10000
	s_addc_u32 s11, s11, 0
	s_add_u32 s14, s14, 0x200
	s_addc_u32 s15, s15, 0
	global_load_dwordx2 v[130:131], v24, s[10:11]
	global_load_dwordx4 v[132:135], v25, s[14:15]
	s_add_u32 s10, s10, 0x10000
	s_addc_u32 s11, s11, 0
	s_add_u32 s14, s14, 0x200
	s_addc_u32 s15, s15, 0
	global_load_dwordx2 v[136:137], v24, s[10:11]
	global_load_dwordx4 v[138:141], v25, s[14:15]
	s_add_u32 s10, s10, 0x10000
	s_addc_u32 s11, s11, 0
	s_add_u32 s14, s14, 0x200
	s_addc_u32 s15, s15, 0
	global_load_dwordx2 v[142:143], v24, s[10:11]
	global_load_dwordx4 v[144:147], v25, s[14:15]
	s_add_u32 s10, s10, 0x10000
	s_addc_u32 s11, s11, 0
	s_add_u32 s14, s14, 0x200
	s_addc_u32 s15, s15, 0
	global_load_dwordx2 v[148:149], v24, s[10:11]
	global_load_dwordx4 v[150:153], v25, s[14:15]
	s_add_u32 s10, s10, 0x10000
	s_addc_u32 s11, s11, 0
	s_add_u32 s14, s14, 0x200
	s_addc_u32 s15, s15, 0
	global_load_dwordx2 v[154:155], v24, s[10:11]
	global_load_dwordx4 v[156:159], v25, s[14:15]
	s_add_u32 s10, s10, 0x10000
	s_addc_u32 s11, s11, 0
	s_add_u32 s14, s14, 0x200
	s_addc_u32 s15, s15, 0
	global_load_dwordx2 v[160:161], v24, s[10:11]
	global_load_dwordx4 v[162:165], v25, s[14:15]
	s_add_u32 s10, s10, 0x10000
	s_addc_u32 s11, s11, 0
	s_add_u32 s14, s14, 0x200
	s_addc_u32 s15, s15, 0
	global_load_dwordx2 v[166:167], v24, s[10:11]
	global_load_dwordx4 v[168:171], v25, s[14:15]
	s_add_u32 s10, s10, 0x10000
	s_addc_u32 s11, s11, 0
	s_add_u32 s14, s14, 0x200
	s_addc_u32 s15, s15, 0
	global_load_dwordx2 v[172:173], v24, s[10:11]
	global_load_dwordx4 v[174:177], v25, s[14:15]
	s_add_u32 s10, s10, 0x10000
	s_addc_u32 s11, s11, 0
	s_add_u32 s14, s14, 0x200
	s_addc_u32 s15, s15, 0
	global_load_dwordx2 v[178:179], v24, s[10:11]
	global_load_dwordx4 v[180:183], v25, s[14:15]
	s_add_u32 s10, s10, 0x10000
	s_addc_u32 s11, s11, 0
	s_add_u32 s14, s14, 0x200
	s_addc_u32 s15, s15, 0
	global_load_dwordx2 v[184:185], v24, s[10:11]
	global_load_dwordx4 v[186:189], v25, s[14:15]
	s_add_u32 s10, s10, 0x10000
	s_addc_u32 s11, s11, 0
	s_add_u32 s14, s14, 0x200
	s_addc_u32 s15, s15, 0
	global_load_dwordx2 v[190:191], v24, s[10:11]
	global_load_dwordx4 v[192:195], v25, s[14:15]
	s_add_u32 s10, s10, 0x10000
	s_addc_u32 s11, s11, 0
	s_add_u32 s14, s14, 0x200
	s_addc_u32 s15, s15, 0
	s_waitcnt vmcnt(30)
; __device__ __forceinline__ unsigned cvt_pk_bf16(float lo, float hi) { unsigned r; asm volatile("v_cvt_pk_bf16_f32 %0, %1, %2" : "=v"(r) : "v"(lo), "v"(hi)); return r; }
; __device__ __forceinline__ float bf_lo(unsigned w) { return __uint_as_float(w << 16); }
; __device__ __forceinline__ float bf_hi(unsigned w) { return __uint_as_float(w & 0xffff0000u); }
; __device__ __forceinline__ void gla_g2(const Params& P, unsigned char* lds) {
;     ...
;         for (int cb = 0; cb < 8; ++cb) {
;             u32x2 kv[8]; f32x4 d[8];
; #pragma unroll
;             for (int j = 0; j < 8; ++j) { const int it = bh * 64 + cb * 8 + j; kv[j] = *(const u32x2*)(KVT + ((size_t)it * 256 + dv) * 128 + dk4); d[j] = *(const f32x4*)(dec + (size_t)it * 128 + dk4); }
; #pragma unroll
;             for (int j = 0; j < 8; ++j) { const int it = bh * 64 + cb * 8 + j; u32x2 w; w.x = cvt_pk_bf16(S[0], S[1]); w.y = cvt_pk_bf16(S[2], S[3]);
;                 *(u32x2*)(KVT + ((size_t)it * 256 + dv) * 128 + dk4) = w;
;                 S[0] = d[j][0] * S[0] + bf_lo(kv[j].x); S[1] = d[j][1] * S[1] + bf_hi(kv[j].x); S[2] = d[j][2] * S[2] + bf_lo(kv[j].y); S[3] = d[j][3] * S[3] + bf_hi(kv[j].y); }
;         }
	v_cvt_pk_bf16_f32 v38, v30, v31
	v_cvt_pk_bf16_f32 v39, v32, v33
	global_store_dwordx2 v24, v[38:39], s[12:13]
	s_add_u32 s12, s12, 0x10000
	s_addc_u32 s13, s13, 0
	v_lshlrev_b32_e32 v34, 16, v100
	v_and_b32_e32 v35, 0xffff0000, v100
	v_lshlrev_b32_e32 v36, 16, v101
	v_and_b32_e32 v37, 0xffff0000, v101
	v_fma_f32 v30, v102, v30, v34
	v_fma_f32 v31, v103, v31, v35
	v_fma_f32 v32, v104, v32, v36
	v_fma_f32 v33, v105, v33, v37
	global_load_dwordx2 v[100:101], v24, s[10:11]
	global_load_dwordx4 v[102:105], v25, s[14:15]
	s_add_u32 s10, s10, 0x10000
	s_addc_u32 s11, s11, 0
	s_add_u32 s14, s14, 0x200
	s_addc_u32 s15, s15, 0
	s_waitcnt vmcnt(31)
	v_cvt_pk_bf16_f32 v40, v30, v31
	v_cvt_pk_bf16_f32 v41, v32, v33
	global_store_dwordx2 v24, v[40:41], s[12:13]
	s_add_u32 s12, s12, 0x10000
	s_addc_u32 s13, s13, 0
	v_lshlrev_b32_e32 v34, 16, v106
	v_and_b32_e32 v35, 0xffff0000, v106
	v_lshlrev_b32_e32 v36, 16, v107
	v_and_b32_e32 v37, 0xffff0000, v107
	v_fma_f32 v30, v108, v30, v34
	v_fma_f32 v31, v109, v31, v35
	v_fma_f32 v32, v110, v32, v36
	v_fma_f32 v33, v111, v33, v37
	global_load_dwordx2 v[106:107], v24, s[10:11]
	global_load_dwordx4 v[108:111], v25, s[14:15]
	s_add_u32 s10, s10, 0x10000
	s_addc_u32 s11, s11, 0
	s_add_u32 s14, s14, 0x200
	s_addc_u32 s15, s15, 0
	s_waitcnt vmcnt(32)
	v_cvt_pk_bf16_f32 v38, v30, v31
	v_cvt_pk_bf16_f32 v39, v32, v33
	global_store_dwordx2 v24, v[38:39], s[12:13]
	s_add_u32 s12, s12, 0x10000
	s_addc_u32 s13, s13, 0
	v_lshlrev_b32_e32 v34, 16, v112
	v_and_b32_e32 v35, 0xffff0000, v112
	v_lshlrev_b32_e32 v36, 16, v113
	v_and_b32_e32 v37, 0xffff0000, v113
	v_fma_f32 v30, v114, v30, v34
	v_fma_f32 v31, v115, v31, v35
	v_fma_f32 v32, v116, v32, v36
	v_fma_f32 v33, v117, v33, v37
	global_load_dwordx2 v[112:113], v24, s[10:11]
	global_load_dwordx4 v[114:117], v25, s[14:15]
	s_add_u32 s10, s10, 0x10000
	s_addc_u32 s11, s11, 0
	s_add_u32 s14, s14, 0x200
	s_addc_u32 s15, s15, 0
	s_waitcnt vmcnt(33)
	v_cvt_pk_bf16_f32 v40, v30, v31
	v_cvt_pk_bf16_f32 v41, v32, v33
	global_store_dwordx2 v24, v[40:41], s[12:13]
	s_add_u32 s12, s12, 0x10000
	s_addc_u32 s13, s13, 0
	v_lshlrev_b32_e32 v34, 16, v118
	v_and_b32_e32 v35, 0xffff0000, v118
	v_lshlrev_b32_e32 v36, 16, v119
	v_and_b32_e32 v37, 0xffff0000, v119
	v_fma_f32 v30, v120, v30, v34
	v_fma_f32 v31, v121, v31, v35
	v_fma_f32 v32, v122, v32, v36
	v_fma_f32 v33, v123, v33, v37
	global_load_dwordx2 v[118:119], v24, s[10:11]
	global_load_dwordx4 v[120:123], v25, s[14:15]
	s_add_u32 s10, s10, 0x10000
	s_addc_u32 s11, s11, 0
	s_add_u32 s14, s14, 0x200
	s_addc_u32 s15, s15, 0
	s_waitcnt vmcnt(34)
	v_cvt_pk_bf16_f32 v38, v30, v31
	v_cvt_pk_bf16_f32 v39, v32, v33
	global_store_dwordx2 v24, v[38:39], s[12:13]
	s_add_u32 s12, s12, 0x10000
	s_addc_u32 s13, s13, 0
	v_lshlrev_b32_e32 v34, 16, v124
	v_and_b32_e32 v35, 0xffff0000, v124
	v_lshlrev_b32_e32 v36, 16, v125
	v_and_b32_e32 v37, 0xffff0000, v125
	v_fma_f32 v30, v126, v30, v34
	v_fma_f32 v31, v127, v31, v35
	v_fma_f32 v32, v128, v32, v36
	v_fma_f32 v33, v129, v33, v37
	global_load_dwordx2 v[124:125], v24, s[10:11]
	global_load_dwordx4 v[126:129], v25, s[14:15]
	s_add_u32 s10, s10, 0x10000
	s_addc_u32 s11, s11, 0
	s_add_u32 s14, s14, 0x200
	s_addc_u32 s15, s15, 0
	s_waitcnt vmcnt(35)
	v_cvt_pk_bf16_f32 v40, v30, v31
	v_cvt_pk_bf16_f32 v41, v32, v33
	global_store_dwordx2 v24, v[40:41], s[12:13]
	s_add_u32 s12, s12, 0x10000
	s_addc_u32 s13, s13, 0
	v_lshlrev_b32_e32 v34, 16, v130
	v_and_b32_e32 v35, 0xffff0000, v130
	v_lshlrev_b32_e32 v36, 16, v131
	v_and_b32_e32 v37, 0xffff0000, v131
	v_fma_f32 v30, v132, v30, v34
	v_fma_f32 v31, v133, v31, v35
	v_fma_f32 v32, v134, v32, v36
	v_fma_f32 v33, v135, v33, v37
	global_load_dwordx2 v[130:131], v24, s[10:11]
	global_load_dwordx4 v[132:135], v25, s[14:15]
	s_add_u32 s10, s10, 0x10000
	s_addc_u32 s11, s11, 0
	s_add_u32 s14, s14, 0x200
	s_addc_u32 s15, s15, 0
	s_waitcnt vmcnt(36)
	v_cvt_pk_bf16_f32 v38, v30, v31
	v_cvt_pk_bf16_f32 v39, v32, v33
	global_store_dwordx2 v24, v[38:39], s[12:13]
	s_add_u32 s12, s12, 0x10000
	s_addc_u32 s13, s13, 0
	v_lshlrev_b32_e32 v34, 16, v136
	v_and_b32_e32 v35, 0xffff0000, v136
	v_lshlrev_b32_e32 v36, 16, v137
	v_and_b32_e32 v37, 0xffff0000, v137
	v_fma_f32 v30, v138, v30, v34
	v_fma_f32 v31, v139, v31, v35
	v_fma_f32 v32, v140, v32, v36
	v_fma_f32 v33, v141, v33, v37
	global_load_dwordx2 v[136:137], v24, s[10:11]
	global_load_dwordx4 v[138:141], v25, s[14:15]
	s_add_u32 s10, s10, 0x10000
	s_addc_u32 s11, s11, 0
	s_add_u32 s14, s14, 0x200
	s_addc_u32 s15, s15, 0
	s_waitcnt vmcnt(37)
	v_cvt_pk_bf16_f32 v40, v30, v31
	v_cvt_pk_bf16_f32 v41, v32, v33
	global_store_dwordx2 v24, v[40:41], s[12:13]
	s_add_u32 s12, s12, 0x10000
	s_addc_u32 s13, s13, 0
	v_lshlrev_b32_e32 v34, 16, v142
	v_and_b32_e32 v35, 0xffff0000, v142
	v_lshlrev_b32_e32 v36, 16, v143
	v_and_b32_e32 v37, 0xffff0000, v143
	v_fma_f32 v30, v144, v30, v34
	v_fma_f32 v31, v145, v31, v35
	v_fma_f32 v32, v146, v32, v36
	v_fma_f32 v33, v147, v33, v37
	global_load_dwordx2 v[142:143], v24, s[10:11]
	global_load_dwordx4 v[144:147], v25, s[14:15]
	s_add_u32 s10, s10, 0x10000
	s_addc_u32 s11, s11, 0
	s_add_u32 s14, s14, 0x200
	s_addc_u32 s15, s15, 0
	s_waitcnt vmcnt(38)
	v_cvt_pk_bf16_f32 v38, v30, v31
	v_cvt_pk_bf16_f32 v39, v32, v33
	global_store_dwordx2 v24, v[38:39], s[12:13]
	s_add_u32 s12, s12, 0x10000
	s_addc_u32 s13, s13, 0
	v_lshlrev_b32_e32 v34, 16, v148
	v_and_b32_e32 v35, 0xffff0000, v148
	v_lshlrev_b32_e32 v36, 16, v149
	v_and_b32_e32 v37, 0xffff0000, v149
	v_fma_f32 v30, v150, v30, v34
	v_fma_f32 v31, v151, v31, v35
	v_fma_f32 v32, v152, v32, v36
	v_fma_f32 v33, v153, v33, v37
	global_load_dwordx2 v[148:149], v24, s[10:11]
	global_load_dwordx4 v[150:153], v25, s[14:15]
	s_add_u32 s10, s10, 0x10000
	s_addc_u32 s11, s11, 0
	s_add_u32 s14, s14, 0x200
	s_addc_u32 s15, s15, 0
	s_waitcnt vmcnt(39)
; __device__ __forceinline__ unsigned cvt_pk_bf16(float lo, float hi) { unsigned r; asm volatile("v_cvt_pk_bf16_f32 %0, %1, %2" : "=v"(r) : "v"(lo), "v"(hi)); return r; }
; __device__ __forceinline__ float bf_lo(unsigned w) { return __uint_as_float(w << 16); }
; __device__ __forceinline__ float bf_hi(unsigned w) { return __uint_as_float(w & 0xffff0000u); }
; __device__ __forceinline__ void gla_g2(const Params& P, unsigned char* lds) {
;     ...
;         for (int cb = 0; cb < 8; ++cb) {
;             u32x2 kv[8]; f32x4 d[8];
; #pragma unroll
;             for (int j = 0; j < 8; ++j) { const int it = bh * 64 + cb * 8 + j; kv[j] = *(const u32x2*)(KVT + ((size_t)it * 256 + dv) * 128 + dk4); d[j] = *(const f32x4*)(dec + (size_t)it * 128 + dk4); }
; #pragma unroll
;             for (int j = 0; j < 8; ++j) { const int it = bh * 64 + cb * 8 + j; u32x2 w; w.x = cvt_pk_bf16(S[0], S[1]); w.y = cvt_pk_bf16(S[2], S[3]);
;                 *(u32x2*)(KVT + ((size_t)it * 256 + dv) * 128 + dk4) = w;
;                 S[0] = d[j][0] * S[0] + bf_lo(kv[j].x); S[1] = d[j][1] * S[1] + bf_hi(kv[j].x); S[2] = d[j][2] * S[2] + bf_lo(kv[j].y); S[3] = d[j][3] * S[3] + bf_hi(kv[j].y); }
;         }
	v_cvt_pk_bf16_f32 v40, v30, v31
	v_cvt_pk_bf16_f32 v41, v32, v33
	global_store_dwordx2 v24, v[40:41], s[12:13]
	s_add_u32 s12, s12, 0x10000
	s_addc_u32 s13, s13, 0
	v_lshlrev_b32_e32 v34, 16, v154
	v_and_b32_e32 v35, 0xffff0000, v154
	v_lshlrev_b32_e32 v36, 16, v155
	v_and_b32_e32 v37, 0xffff0000, v155
	v_fma_f32 v30, v156, v30, v34
	v_fma_f32 v31, v157, v31, v35
	v_fma_f32 v32, v158, v32, v36
	v_fma_f32 v33, v159, v33, v37
	global_load_dwordx2 v[154:155], v24, s[10:11]
	global_load_dwordx4 v[156:159], v25, s[14:15]
	s_add_u32 s10, s10, 0x10000
	s_addc_u32 s11, s11, 0
	s_add_u32 s14, s14, 0x200
	s_addc_u32 s15, s15, 0
	s_waitcnt vmcnt(40)
	v_cvt_pk_bf16_f32 v38, v30, v31
	v_cvt_pk_bf16_f32 v39, v32, v33
	global_store_dwordx2 v24, v[38:39], s[12:13]
	s_add_u32 s12, s12, 0x10000
	s_addc_u32 s13, s13, 0
	v_lshlrev_b32_e32 v34, 16, v160
	v_and_b32_e32 v35, 0xffff0000, v160
	v_lshlrev_b32_e32 v36, 16, v161
	v_and_b32_e32 v37, 0xffff0000, v161
	v_fma_f32 v30, v162, v30, v34
	v_fma_f32 v31, v163, v31, v35
	v_fma_f32 v32, v164, v32, v36
	v_fma_f32 v33, v165, v33, v37
	global_load_dwordx2 v[160:161], v24, s[10:11]
	global_load_dwordx4 v[162:165], v25, s[14:15]
	s_add_u32 s10, s10, 0x10000
	s_addc_u32 s11, s11, 0
	s_add_u32 s14, s14, 0x200
	s_addc_u32 s15, s15, 0
	s_waitcnt vmcnt(41)
	v_cvt_pk_bf16_f32 v40, v30, v31
	v_cvt_pk_bf16_f32 v41, v32, v33
	global_store_dwordx2 v24, v[40:41], s[12:13]
	s_add_u32 s12, s12, 0x10000
	s_addc_u32 s13, s13, 0
	v_lshlrev_b32_e32 v34, 16, v166
	v_and_b32_e32 v35, 0xffff0000, v166
	v_lshlrev_b32_e32 v36, 16, v167
	v_and_b32_e32 v37, 0xffff0000, v167
	v_fma_f32 v30, v168, v30, v34
	v_fma_f32 v31, v169, v31, v35
	v_fma_f32 v32, v170, v32, v36
	v_fma_f32 v33, v171, v33, v37
	global_load_dwordx2 v[166:167], v24, s[10:11]
	global_load_dwordx4 v[168:171], v25, s[14:15]
	s_add_u32 s10, s10, 0x10000
	s_addc_u32 s11, s11, 0
	s_add_u32 s14, s14, 0x200
	s_addc_u32 s15, s15, 0
	s_waitcnt vmcnt(42)
	v_cvt_pk_bf16_f32 v38, v30, v31
	v_cvt_pk_bf16_f32 v39, v32, v33
	global_store_dwordx2 v24, v[38:39], s[12:13]
	s_add_u32 s12, s12, 0x10000
	s_addc_u32 s13, s13, 0
	v_lshlrev_b32_e32 v34, 16, v172
	v_and_b32_e32 v35, 0xffff0000, v172
	v_lshlrev_b32_e32 v36, 16, v173
	v_and_b32_e32 v37, 0xffff0000, v173
	v_fma_f32 v30, v174, v30, v34
	v_fma_f32 v31, v175, v31, v35
	v_fma_f32 v32, v176, v32, v36
	v_fma_f32 v33, v177, v33, v37
	global_load_dwordx2 v[172:173], v24, s[10:11]
	global_load_dwordx4 v[174:177], v25, s[14:15]
	s_add_u32 s10, s10, 0x10000
	s_addc_u32 s11, s11, 0
	s_add_u32 s14, s14, 0x200
	s_addc_u32 s15, s15, 0
	s_waitcnt vmcnt(43)
	v_cvt_pk_bf16_f32 v40, v30, v31
	v_cvt_pk_bf16_f32 v41, v32, v33
	global_store_dwordx2 v24, v[40:41], s[12:13]
	s_add_u32 s12, s12, 0x10000
	s_addc_u32 s13, s13, 0
	v_lshlrev_b32_e32 v34, 16, v178
	v_and_b32_e32 v35, 0xffff0000, v178
	v_lshlrev_b32_e32 v36, 16, v179
	v_and_b32_e32 v37, 0xffff0000, v179
	v_fma_f32 v30, v180, v30, v34
	v_fma_f32 v31, v181, v31, v35
	v_fma_f32 v32, v182, v32, v36
	v_fma_f32 v33, v183, v33, v37
	global_load_dwordx2 v[178:179], v24, s[10:11]
	global_load_dwordx4 v[180:183], v25, s[14:15]
	s_add_u32 s10, s10, 0x10000
	s_addc_u32 s11, s11, 0
	s_add_u32 s14, s14, 0x200
	s_addc_u32 s15, s15, 0
	s_waitcnt vmcnt(44)
	v_cvt_pk_bf16_f32 v38, v30, v31
	v_cvt_pk_bf16_f32 v39, v32, v33
	global_store_dwordx2 v24, v[38:39], s[12:13]
	s_add_u32 s12, s12, 0x10000
	s_addc_u32 s13, s13, 0
	v_lshlrev_b32_e32 v34, 16, v184
	v_and_b32_e32 v35, 0xffff0000, v184
	v_lshlrev_b32_e32 v36, 16, v185
	v_and_b32_e32 v37, 0xffff0000, v185
	v_fma_f32 v30, v186, v30, v34
	v_fma_f32 v31, v187, v31, v35
	v_fma_f32 v32, v188, v32, v36
	v_fma_f32 v33, v189, v33, v37
	global_load_dwordx2 v[184:185], v24, s[10:11]
	global_load_dwordx4 v[186:189], v25, s[14:15]
	s_add_u32 s10, s10, 0x10000
	s_addc_u32 s11, s11, 0
	s_add_u32 s14, s14, 0x200
	s_addc_u32 s15, s15, 0
	s_waitcnt vmcnt(45)
	v_cvt_pk_bf16_f32 v40, v30, v31
	v_cvt_pk_bf16_f32 v41, v32, v33
	global_store_dwordx2 v24, v[40:41], s[12:13]
	s_add_u32 s12, s12, 0x10000
	s_addc_u32 s13, s13, 0
	v_lshlrev_b32_e32 v34, 16, v190
	v_and_b32_e32 v35, 0xffff0000, v190
	v_lshlrev_b32_e32 v36, 16, v191
	v_and_b32_e32 v37, 0xffff0000, v191
	v_fma_f32 v30, v192, v30, v34
	v_fma_f32 v31, v193, v31, v35
	v_fma_f32 v32, v194, v32, v36
	v_fma_f32 v33, v195, v33, v37
	global_load_dwordx2 v[190:191], v24, s[10:11]
	global_load_dwordx4 v[192:195], v25, s[14:15]
	s_add_u32 s10, s10, 0x10000
	s_addc_u32 s11, s11, 0
	s_add_u32 s14, s14, 0x200
	s_addc_u32 s15, s15, 0
	s_waitcnt vmcnt(45)
	v_cvt_pk_bf16_f32 v38, v30, v31
	v_cvt_pk_bf16_f32 v39, v32, v33
	global_store_dwordx2 v24, v[38:39], s[12:13]
	s_add_u32 s12, s12, 0x10000
	s_addc_u32 s13, s13, 0
	v_lshlrev_b32_e32 v34, 16, v100
	v_and_b32_e32 v35, 0xffff0000, v100
	v_lshlrev_b32_e32 v36, 16, v101
	v_and_b32_e32 v37, 0xffff0000, v101
	v_fma_f32 v30, v102, v30, v34
	v_fma_f32 v31, v103, v31, v35
	v_fma_f32 v32, v104, v32, v36
	v_fma_f32 v33, v105, v33, v37
	global_load_dwordx2 v[100:101], v24, s[10:11]
	global_load_dwordx4 v[102:105], v25, s[14:15]
	s_add_u32 s10, s10, 0x10000
	s_addc_u32 s11, s11, 0
	s_add_u32 s14, s14, 0x200
	s_addc_u32 s15, s15, 0
	s_waitcnt vmcnt(45)
	v_cvt_pk_bf16_f32 v40, v30, v31
	v_cvt_pk_bf16_f32 v41, v32, v33
	global_store_dwordx2 v24, v[40:41], s[12:13]
	s_add_u32 s12, s12, 0x10000
	s_addc_u32 s13, s13, 0
	v_lshlrev_b32_e32 v34, 16, v106
	v_and_b32_e32 v35, 0xffff0000, v106
	v_lshlrev_b32_e32 v36, 16, v107
	v_and_b32_e32 v37, 0xffff0000, v107
	v_fma_f32 v30, v108, v30, v34
	v_fma_f32 v31, v109, v31, v35
	v_fma_f32 v32, v110, v32, v36
	v_fma_f32 v33, v111, v33, v37
	global_load_dwordx2 v[106:107], v24, s[10:11]
	global_load_dwordx4 v[108:111], v25, s[14:15]
	s_add_u32 s10, s10, 0x10000
	s_addc_u32 s11, s11, 0
	s_add_u32 s14, s14, 0x200
	s_addc_u32 s15, s15, 0
	s_waitcnt vmcnt(45)
; __device__ __forceinline__ unsigned cvt_pk_bf16(float lo, float hi) { unsigned r; asm volatile("v_cvt_pk_bf16_f32 %0, %1, %2" : "=v"(r) : "v"(lo), "v"(hi)); return r; }
; __device__ __forceinline__ float bf_lo(unsigned w) { return __uint_as_float(w << 16); }
; __device__ __forceinline__ float bf_hi(unsigned w) { return __uint_as_float(w & 0xffff0000u); }
; __device__ __forceinline__ void gla_g2(const Params& P, unsigned char* lds) {
;     ...
;         for (int cb = 0; cb < 8; ++cb) {
;             u32x2 kv[8]; f32x4 d[8];
; #pragma unroll
;             for (int j = 0; j < 8; ++j) { const int it = bh * 64 + cb * 8 + j; kv[j] = *(const u32x2*)(KVT + ((size_t)it * 256 + dv) * 128 + dk4); d[j] = *(const f32x4*)(dec + (size_t)it * 128 + dk4); }
; #pragma unroll
;             for (int j = 0; j < 8; ++j) { const int it = bh * 64 + cb * 8 + j; u32x2 w; w.x = cvt_pk_bf16(S[0], S[1]); w.y = cvt_pk_bf16(S[2], S[3]);
;                 *(u32x2*)(KVT + ((size_t)it * 256 + dv) * 128 + dk4) = w;
;                 S[0] = d[j][0] * S[0] + bf_lo(kv[j].x); S[1] = d[j][1] * S[1] + bf_hi(kv[j].x); S[2] = d[j][2] * S[2] + bf_lo(kv[j].y); S[3] = d[j][3] * S[3] + bf_hi(kv[j].y); }
;         }
	v_cvt_pk_bf16_f32 v38, v30, v31
	v_cvt_pk_bf16_f32 v39, v32, v33
	global_store_dwordx2 v24, v[38:39], s[12:13]
	s_add_u32 s12, s12, 0x10000
	s_addc_u32 s13, s13, 0
	v_lshlrev_b32_e32 v34, 16, v112
	v_and_b32_e32 v35, 0xffff0000, v112
	v_lshlrev_b32_e32 v36, 16, v113
	v_and_b32_e32 v37, 0xffff0000, v113
	v_fma_f32 v30, v114, v30, v34
	v_fma_f32 v31, v115, v31, v35
	v_fma_f32 v32, v116, v32, v36
	v_fma_f32 v33, v117, v33, v37
	global_load_dwordx2 v[112:113], v24, s[10:11]
	global_load_dwordx4 v[114:117], v25, s[14:15]
	s_add_u32 s10, s10, 0x10000
	s_addc_u32 s11, s11, 0
	s_add_u32 s14, s14, 0x200
	s_addc_u32 s15, s15, 0
	s_waitcnt vmcnt(45)
	v_cvt_pk_bf16_f32 v40, v30, v31
	v_cvt_pk_bf16_f32 v41, v32, v33
	global_store_dwordx2 v24, v[40:41], s[12:13]
	s_add_u32 s12, s12, 0x10000
	s_addc_u32 s13, s13, 0
	v_lshlrev_b32_e32 v34, 16, v118
	v_and_b32_e32 v35, 0xffff0000, v118
	v_lshlrev_b32_e32 v36, 16, v119
	v_and_b32_e32 v37, 0xffff0000, v119
	v_fma_f32 v30, v120, v30, v34
	v_fma_f32 v31, v121, v31, v35
	v_fma_f32 v32, v122, v32, v36
	v_fma_f32 v33, v123, v33, v37
	global_load_dwordx2 v[118:119], v24, s[10:11]
	global_load_dwordx4 v[120:123], v25, s[14:15]
	s_add_u32 s10, s10, 0x10000
	s_addc_u32 s11, s11, 0
	s_add_u32 s14, s14, 0x200
	s_addc_u32 s15, s15, 0
	s_waitcnt vmcnt(45)
	v_cvt_pk_bf16_f32 v38, v30, v31
	v_cvt_pk_bf16_f32 v39, v32, v33
	global_store_dwordx2 v24, v[38:39], s[12:13]
	s_add_u32 s12, s12, 0x10000
	s_addc_u32 s13, s13, 0
	v_lshlrev_b32_e32 v34, 16, v124
	v_and_b32_e32 v35, 0xffff0000, v124
	v_lshlrev_b32_e32 v36, 16, v125
	v_and_b32_e32 v37, 0xffff0000, v125
	v_fma_f32 v30, v126, v30, v34
	v_fma_f32 v31, v127, v31, v35
	v_fma_f32 v32, v128, v32, v36
	v_fma_f32 v33, v129, v33, v37
	global_load_dwordx2 v[124:125], v24, s[10:11]
	global_load_dwordx4 v[126:129], v25, s[14:15]
	s_add_u32 s10, s10, 0x10000
	s_addc_u32 s11, s11, 0
	s_add_u32 s14, s14, 0x200
	s_addc_u32 s15, s15, 0
	s_waitcnt vmcnt(45)
	v_cvt_pk_bf16_f32 v40, v30, v31
	v_cvt_pk_bf16_f32 v41, v32, v33
	global_store_dwordx2 v24, v[40:41], s[12:13]
	s_add_u32 s12, s12, 0x10000
	s_addc_u32 s13, s13, 0
	v_lshlrev_b32_e32 v34, 16, v130
	v_and_b32_e32 v35, 0xffff0000, v130
	v_lshlrev_b32_e32 v36, 16, v131
	v_and_b32_e32 v37, 0xffff0000, v131
	v_fma_f32 v30, v132, v30, v34
	v_fma_f32 v31, v133, v31, v35
	v_fma_f32 v32, v134, v32, v36
	v_fma_f32 v33, v135, v33, v37
	global_load_dwordx2 v[130:131], v24, s[10:11]
	global_load_dwordx4 v[132:135], v25, s[14:15]
	s_add_u32 s10, s10, 0x10000
	s_addc_u32 s11, s11, 0
	s_add_u32 s14, s14, 0x200
	s_addc_u32 s15, s15, 0
	s_waitcnt vmcnt(45)
	v_cvt_pk_bf16_f32 v38, v30, v31
	v_cvt_pk_bf16_f32 v39, v32, v33
	global_store_dwordx2 v24, v[38:39], s[12:13]
	s_add_u32 s12, s12, 0x10000
	s_addc_u32 s13, s13, 0
	v_lshlrev_b32_e32 v34, 16, v136
	v_and_b32_e32 v35, 0xffff0000, v136
	v_lshlrev_b32_e32 v36, 16, v137
	v_and_b32_e32 v37, 0xffff0000, v137
	v_fma_f32 v30, v138, v30, v34
	v_fma_f32 v31, v139, v31, v35
	v_fma_f32 v32, v140, v32, v36
	v_fma_f32 v33, v141, v33, v37
	global_load_dwordx2 v[136:137], v24, s[10:11]
	global_load_dwordx4 v[138:141], v25, s[14:15]
	s_add_u32 s10, s10, 0x10000
	s_addc_u32 s11, s11, 0
	s_add_u32 s14, s14, 0x200
	s_addc_u32 s15, s15, 0
	s_waitcnt vmcnt(45)
	v_cvt_pk_bf16_f32 v40, v30, v31
	v_cvt_pk_bf16_f32 v41, v32, v33
	global_store_dwordx2 v24, v[40:41], s[12:13]
	s_add_u32 s12, s12, 0x10000
	s_addc_u32 s13, s13, 0
	v_lshlrev_b32_e32 v34, 16, v142
	v_and_b32_e32 v35, 0xffff0000, v142
	v_lshlrev_b32_e32 v36, 16, v143
	v_and_b32_e32 v37, 0xffff0000, v143
	v_fma_f32 v30, v144, v30, v34
	v_fma_f32 v31, v145, v31, v35
	v_fma_f32 v32, v146, v32, v36
	v_fma_f32 v33, v147, v33, v37
	global_load_dwordx2 v[142:143], v24, s[10:11]
	global_load_dwordx4 v[144:147], v25, s[14:15]
	s_add_u32 s10, s10, 0x10000
	s_addc_u32 s11, s11, 0
	s_add_u32 s14, s14, 0x200
	s_addc_u32 s15, s15, 0
	s_waitcnt vmcnt(45)
	v_cvt_pk_bf16_f32 v38, v30, v31
	v_cvt_pk_bf16_f32 v39, v32, v33
	global_store_dwordx2 v24, v[38:39], s[12:13]
	s_add_u32 s12, s12, 0x10000
	s_addc_u32 s13, s13, 0
	v_lshlrev_b32_e32 v34, 16, v148
	v_and_b32_e32 v35, 0xffff0000, v148
	v_lshlrev_b32_e32 v36, 16, v149
	v_and_b32_e32 v37, 0xffff0000, v149
	v_fma_f32 v30, v150, v30, v34
	v_fma_f32 v31, v151, v31, v35
	v_fma_f32 v32, v152, v32, v36
	v_fma_f32 v33, v153, v33, v37
	global_load_dwordx2 v[148:149], v24, s[10:11]
	global_load_dwordx4 v[150:153], v25, s[14:15]
	s_add_u32 s10, s10, 0x10000
	s_addc_u32 s11, s11, 0
	s_add_u32 s14, s14, 0x200
	s_addc_u32 s15, s15, 0
	s_waitcnt vmcnt(45)
	v_cvt_pk_bf16_f32 v40, v30, v31
	v_cvt_pk_bf16_f32 v41, v32, v33
	global_store_dwordx2 v24, v[40:41], s[12:13]
	s_add_u32 s12, s12, 0x10000
	s_addc_u32 s13, s13, 0
	v_lshlrev_b32_e32 v34, 16, v154
	v_and_b32_e32 v35, 0xffff0000, v154
	v_lshlrev_b32_e32 v36, 16, v155
	v_and_b32_e32 v37, 0xffff0000, v155
	v_fma_f32 v30, v156, v30, v34
	v_fma_f32 v31, v157, v31, v35
	v_fma_f32 v32, v158, v32, v36
	v_fma_f32 v33, v159, v33, v37
	global_load_dwordx2 v[154:155], v24, s[10:11]
	global_load_dwordx4 v[156:159], v25, s[14:15]
	s_add_u32 s10, s10, 0x10000
	s_addc_u32 s11, s11, 0
	s_add_u32 s14, s14, 0x200
	s_addc_u32 s15, s15, 0
	s_waitcnt vmcnt(45)
	v_cvt_pk_bf16_f32 v38, v30, v31
	v_cvt_pk_bf16_f32 v39, v32, v33
	global_store_dwordx2 v24, v[38:39], s[12:13]
	s_add_u32 s12, s12, 0x10000
	s_addc_u32 s13, s13, 0
	v_lshlrev_b32_e32 v34, 16, v160
	v_and_b32_e32 v35, 0xffff0000, v160
	v_lshlrev_b32_e32 v36, 16, v161
	v_and_b32_e32 v37, 0xffff0000, v161
	v_fma_f32 v30, v162, v30, v34
	v_fma_f32 v31, v163, v31, v35
	v_fma_f32 v32, v164, v32, v36
	v_fma_f32 v33, v165, v33, v37
	global_load_dwordx2 v[160:161], v24, s[10:11]
	global_load_dwordx4 v[162:165], v25, s[14:15]
	s_add_u32 s10, s10, 0x10000
	s_addc_u32 s11, s11, 0
	s_add_u32 s14, s14, 0x200
	s_addc_u32 s15, s15, 0
	s_waitcnt vmcnt(45)
; __device__ __forceinline__ unsigned cvt_pk_bf16(float lo, float hi) { unsigned r; asm volatile("v_cvt_pk_bf16_f32 %0, %1, %2" : "=v"(r) : "v"(lo), "v"(hi)); return r; }
; __device__ __forceinline__ float bf_lo(unsigned w) { return __uint_as_float(w << 16); }
; __device__ __forceinline__ float bf_hi(unsigned w) { return __uint_as_float(w & 0xffff0000u); }
; __device__ __forceinline__ void gla_g2(const Params& P, unsigned char* lds) {
;     ...
;         for (int cb = 0; cb < 8; ++cb) {
;             u32x2 kv[8]; f32x4 d[8];
; #pragma unroll
;             for (int j = 0; j < 8; ++j) { const int it = bh * 64 + cb * 8 + j; kv[j] = *(const u32x2*)(KVT + ((size_t)it * 256 + dv) * 128 + dk4); d[j] = *(const f32x4*)(dec + (size_t)it * 128 + dk4); }
; #pragma unroll
;             for (int j = 0; j < 8; ++j) { const int it = bh * 64 + cb * 8 + j; u32x2 w; w.x = cvt_pk_bf16(S[0], S[1]); w.y = cvt_pk_bf16(S[2], S[3]);
;                 *(u32x2*)(KVT + ((size_t)it * 256 + dv) * 128 + dk4) = w;
;                 S[0] = d[j][0] * S[0] + bf_lo(kv[j].x); S[1] = d[j][1] * S[1] + bf_hi(kv[j].x); S[2] = d[j][2] * S[2] + bf_lo(kv[j].y); S[3] = d[j][3] * S[3] + bf_hi(kv[j].y); }
;         }
	v_cvt_pk_bf16_f32 v40, v30, v31
	v_cvt_pk_bf16_f32 v41, v32, v33
	global_store_dwordx2 v24, v[40:41], s[12:13]
	s_add_u32 s12, s12, 0x10000
	s_addc_u32 s13, s13, 0
	v_lshlrev_b32_e32 v34, 16, v166
	v_and_b32_e32 v35, 0xffff0000, v166
	v_lshlrev_b32_e32 v36, 16, v167
	v_and_b32_e32 v37, 0xffff0000, v167
	v_fma_f32 v30, v168, v30, v34
	v_fma_f32 v31, v169, v31, v35
	v_fma_f32 v32, v170, v32, v36
	v_fma_f32 v33, v171, v33, v37
	global_load_dwordx2 v[166:167], v24, s[10:11]
	global_load_dwordx4 v[168:171], v25, s[14:15]
	s_add_u32 s10, s10, 0x10000
	s_addc_u32 s11, s11, 0
	s_add_u32 s14, s14, 0x200
	s_addc_u32 s15, s15, 0
	s_waitcnt vmcnt(45)
	v_cvt_pk_bf16_f32 v38, v30, v31
	v_cvt_pk_bf16_f32 v39, v32, v33
	global_store_dwordx2 v24, v[38:39], s[12:13]
	s_add_u32 s12, s12, 0x10000
	s_addc_u32 s13, s13, 0
	v_lshlrev_b32_e32 v34, 16, v172
	v_and_b32_e32 v35, 0xffff0000, v172
	v_lshlrev_b32_e32 v36, 16, v173
	v_and_b32_e32 v37, 0xffff0000, v173
	v_fma_f32 v30, v174, v30, v34
	v_fma_f32 v31, v175, v31, v35
	v_fma_f32 v32, v176, v32, v36
	v_fma_f32 v33, v177, v33, v37
	global_load_dwordx2 v[172:173], v24, s[10:11]
	global_load_dwordx4 v[174:177], v25, s[14:15]
	s_add_u32 s10, s10, 0x10000
	s_addc_u32 s11, s11, 0
	s_add_u32 s14, s14, 0x200
	s_addc_u32 s15, s15, 0
	s_waitcnt vmcnt(45)
	v_cvt_pk_bf16_f32 v40, v30, v31
	v_cvt_pk_bf16_f32 v41, v32, v33
	global_store_dwordx2 v24, v[40:41], s[12:13]
	s_add_u32 s12, s12, 0x10000
	s_addc_u32 s13, s13, 0
	v_lshlrev_b32_e32 v34, 16, v178
	v_and_b32_e32 v35, 0xffff0000, v178
	v_lshlrev_b32_e32 v36, 16, v179
	v_and_b32_e32 v37, 0xffff0000, v179
	v_fma_f32 v30, v180, v30, v34
	v_fma_f32 v31, v181, v31, v35
	v_fma_f32 v32, v182, v32, v36
	v_fma_f32 v33, v183, v33, v37
	global_load_dwordx2 v[178:179], v24, s[10:11]
	global_load_dwordx4 v[180:183], v25, s[14:15]
	s_add_u32 s10, s10, 0x10000
	s_addc_u32 s11, s11, 0
	s_add_u32 s14, s14, 0x200
	s_addc_u32 s15, s15, 0
	s_waitcnt vmcnt(45)
	v_cvt_pk_bf16_f32 v38, v30, v31
	v_cvt_pk_bf16_f32 v39, v32, v33
	global_store_dwordx2 v24, v[38:39], s[12:13]
	s_add_u32 s12, s12, 0x10000
	s_addc_u32 s13, s13, 0
	v_lshlrev_b32_e32 v34, 16, v184
	v_and_b32_e32 v35, 0xffff0000, v184
	v_lshlrev_b32_e32 v36, 16, v185
	v_and_b32_e32 v37, 0xffff0000, v185
	v_fma_f32 v30, v186, v30, v34
	v_fma_f32 v31, v187, v31, v35
	v_fma_f32 v32, v188, v32, v36
	v_fma_f32 v33, v189, v33, v37
	global_load_dwordx2 v[184:185], v24, s[10:11]
	global_load_dwordx4 v[186:189], v25, s[14:15]
	s_add_u32 s10, s10, 0x10000
	s_addc_u32 s11, s11, 0
	s_add_u32 s14, s14, 0x200
	s_addc_u32 s15, s15, 0
	s_waitcnt vmcnt(45)
	v_cvt_pk_bf16_f32 v40, v30, v31
	v_cvt_pk_bf16_f32 v41, v32, v33
	global_store_dwordx2 v24, v[40:41], s[12:13]
	s_add_u32 s12, s12, 0x10000
	s_addc_u32 s13, s13, 0
	v_lshlrev_b32_e32 v34, 16, v190
	v_and_b32_e32 v35, 0xffff0000, v190
	v_lshlrev_b32_e32 v36, 16, v191
	v_and_b32_e32 v37, 0xffff0000, v191
	v_fma_f32 v30, v192, v30, v34
	v_fma_f32 v31, v193, v31, v35
	v_fma_f32 v32, v194, v32, v36
	v_fma_f32 v33, v195, v33, v37
	global_load_dwordx2 v[190:191], v24, s[10:11]
	global_load_dwordx4 v[192:195], v25, s[14:15]
	s_add_u32 s10, s10, 0x10000
	s_addc_u32 s11, s11, 0
	s_add_u32 s14, s14, 0x200
	s_addc_u32 s15, s15, 0
	s_waitcnt vmcnt(45)
	v_cvt_pk_bf16_f32 v38, v30, v31
	v_cvt_pk_bf16_f32 v39, v32, v33
	global_store_dwordx2 v24, v[38:39], s[12:13]
	s_add_u32 s12, s12, 0x10000
	s_addc_u32 s13, s13, 0
	v_lshlrev_b32_e32 v34, 16, v100
	v_and_b32_e32 v35, 0xffff0000, v100
	v_lshlrev_b32_e32 v36, 16, v101
	v_and_b32_e32 v37, 0xffff0000, v101
	v_fma_f32 v30, v102, v30, v34
	v_fma_f32 v31, v103, v31, v35
	v_fma_f32 v32, v104, v32, v36
	v_fma_f32 v33, v105, v33, v37
	global_load_dwordx2 v[100:101], v24, s[10:11]
	global_load_dwordx4 v[102:105], v25, s[14:15]
	s_add_u32 s10, s10, 0x10000
	s_addc_u32 s11, s11, 0
	s_add_u32 s14, s14, 0x200
	s_addc_u32 s15, s15, 0
	s_waitcnt vmcnt(45)
	v_cvt_pk_bf16_f32 v40, v30, v31
	v_cvt_pk_bf16_f32 v41, v32, v33
	global_store_dwordx2 v24, v[40:41], s[12:13]
	s_add_u32 s12, s12, 0x10000
	s_addc_u32 s13, s13, 0
	v_lshlrev_b32_e32 v34, 16, v106
	v_and_b32_e32 v35, 0xffff0000, v106
	v_lshlrev_b32_e32 v36, 16, v107
	v_and_b32_e32 v37, 0xffff0000, v107
	v_fma_f32 v30, v108, v30, v34
	v_fma_f32 v31, v109, v31, v35
	v_fma_f32 v32, v110, v32, v36
	v_fma_f32 v33, v111, v33, v37
	global_load_dwordx2 v[106:107], v24, s[10:11]
	global_load_dwordx4 v[108:111], v25, s[14:15]
	s_add_u32 s10, s10, 0x10000
	s_addc_u32 s11, s11, 0
	s_add_u32 s14, s14, 0x200
	s_addc_u32 s15, s15, 0
	s_waitcnt vmcnt(45)
	v_cvt_pk_bf16_f32 v38, v30, v31
	v_cvt_pk_bf16_f32 v39, v32, v33
	global_store_dwordx2 v24, v[38:39], s[12:13]
	s_add_u32 s12, s12, 0x10000
	s_addc_u32 s13, s13, 0
	v_lshlrev_b32_e32 v34, 16, v112
	v_and_b32_e32 v35, 0xffff0000, v112
	v_lshlrev_b32_e32 v36, 16, v113
	v_and_b32_e32 v37, 0xffff0000, v113
	v_fma_f32 v30, v114, v30, v34
	v_fma_f32 v31, v115, v31, v35
	v_fma_f32 v32, v116, v32, v36
	v_fma_f32 v33, v117, v33, v37
	global_load_dwordx2 v[112:113], v24, s[10:11]
	global_load_dwordx4 v[114:117], v25, s[14:15]
	s_add_u32 s10, s10, 0x10000
	s_addc_u32 s11, s11, 0
	s_add_u32 s14, s14, 0x200
	s_addc_u32 s15, s15, 0
	s_waitcnt vmcnt(45)
	v_cvt_pk_bf16_f32 v40, v30, v31
	v_cvt_pk_bf16_f32 v41, v32, v33
	global_store_dwordx2 v24, v[40:41], s[12:13]
	s_add_u32 s12, s12, 0x10000
	s_addc_u32 s13, s13, 0
	v_lshlrev_b32_e32 v34, 16, v118
	v_and_b32_e32 v35, 0xffff0000, v118
	v_lshlrev_b32_e32 v36, 16, v119
	v_and_b32_e32 v37, 0xffff0000, v119
	v_fma_f32 v30, v120, v30, v34
	v_fma_f32 v31, v121, v31, v35
	v_fma_f32 v32, v122, v32, v36
	v_fma_f32 v33, v123, v33, v37
	global_load_dwordx2 v[118:119], v24, s[10:11]
	global_load_dwordx4 v[120:123], v25, s[14:15]
	s_add_u32 s10, s10, 0x10000
	s_addc_u32 s11, s11, 0
	s_add_u32 s14, s14, 0x200
	s_addc_u32 s15, s15, 0
	s_waitcnt vmcnt(45)
; __device__ __forceinline__ unsigned cvt_pk_bf16(float lo, float hi) { unsigned r; asm volatile("v_cvt_pk_bf16_f32 %0, %1, %2" : "=v"(r) : "v"(lo), "v"(hi)); return r; }
; __device__ __forceinline__ float bf_lo(unsigned w) { return __uint_as_float(w << 16); }
; __device__ __forceinline__ float bf_hi(unsigned w) { return __uint_as_float(w & 0xffff0000u); }
; __device__ __forceinline__ void gla_g2(const Params& P, unsigned char* lds) {
;     ...
;         for (int cb = 0; cb < 8; ++cb) {
;             u32x2 kv[8]; f32x4 d[8];
; #pragma unroll
;             for (int j = 0; j < 8; ++j) { const int it = bh * 64 + cb * 8 + j; kv[j] = *(const u32x2*)(KVT + ((size_t)it * 256 + dv) * 128 + dk4); d[j] = *(const f32x4*)(dec + (size_t)it * 128 + dk4); }
; #pragma unroll
;             for (int j = 0; j < 8; ++j) { const int it = bh * 64 + cb * 8 + j; u32x2 w; w.x = cvt_pk_bf16(S[0], S[1]); w.y = cvt_pk_bf16(S[2], S[3]);
;                 *(u32x2*)(KVT + ((size_t)it * 256 + dv) * 128 + dk4) = w;
;                 S[0] = d[j][0] * S[0] + bf_lo(kv[j].x); S[1] = d[j][1] * S[1] + bf_hi(kv[j].x); S[2] = d[j][2] * S[2] + bf_lo(kv[j].y); S[3] = d[j][3] * S[3] + bf_hi(kv[j].y); }
;         }
	v_cvt_pk_bf16_f32 v38, v30, v31
	v_cvt_pk_bf16_f32 v39, v32, v33
	global_store_dwordx2 v24, v[38:39], s[12:13]
	s_add_u32 s12, s12, 0x10000
	s_addc_u32 s13, s13, 0
	v_lshlrev_b32_e32 v34, 16, v124
	v_and_b32_e32 v35, 0xffff0000, v124
	v_lshlrev_b32_e32 v36, 16, v125
	v_and_b32_e32 v37, 0xffff0000, v125
	v_fma_f32 v30, v126, v30, v34
	v_fma_f32 v31, v127, v31, v35
	v_fma_f32 v32, v128, v32, v36
	v_fma_f32 v33, v129, v33, v37
	global_load_dwordx2 v[124:125], v24, s[10:11]
	global_load_dwordx4 v[126:129], v25, s[14:15]
	s_add_u32 s10, s10, 0x10000
	s_addc_u32 s11, s11, 0
	s_add_u32 s14, s14, 0x200
	s_addc_u32 s15, s15, 0
	s_waitcnt vmcnt(45)
	v_cvt_pk_bf16_f32 v40, v30, v31
	v_cvt_pk_bf16_f32 v41, v32, v33
	global_store_dwordx2 v24, v[40:41], s[12:13]
	s_add_u32 s12, s12, 0x10000
	s_addc_u32 s13, s13, 0
	v_lshlrev_b32_e32 v34, 16, v130
	v_and_b32_e32 v35, 0xffff0000, v130
	v_lshlrev_b32_e32 v36, 16, v131
	v_and_b32_e32 v37, 0xffff0000, v131
	v_fma_f32 v30, v132, v30, v34
	v_fma_f32 v31, v133, v31, v35
	v_fma_f32 v32, v134, v32, v36
	v_fma_f32 v33, v135, v33, v37
	global_load_dwordx2 v[130:131], v24, s[10:11]
	global_load_dwordx4 v[132:135], v25, s[14:15]
	s_add_u32 s10, s10, 0x10000
	s_addc_u32 s11, s11, 0
	s_add_u32 s14, s14, 0x200
	s_addc_u32 s15, s15, 0
	s_waitcnt vmcnt(45)
	v_cvt_pk_bf16_f32 v38, v30, v31
	v_cvt_pk_bf16_f32 v39, v32, v33
	global_store_dwordx2 v24, v[38:39], s[12:13]
	s_add_u32 s12, s12, 0x10000
	s_addc_u32 s13, s13, 0
	v_lshlrev_b32_e32 v34, 16, v136
	v_and_b32_e32 v35, 0xffff0000, v136
	v_lshlrev_b32_e32 v36, 16, v137
	v_and_b32_e32 v37, 0xffff0000, v137
	v_fma_f32 v30, v138, v30, v34
	v_fma_f32 v31, v139, v31, v35
	v_fma_f32 v32, v140, v32, v36
	v_fma_f32 v33, v141, v33, v37
	global_load_dwordx2 v[136:137], v24, s[10:11]
	global_load_dwordx4 v[138:141], v25, s[14:15]
	s_add_u32 s10, s10, 0x10000
	s_addc_u32 s11, s11, 0
	s_add_u32 s14, s14, 0x200
	s_addc_u32 s15, s15, 0
	s_waitcnt vmcnt(45)
	v_cvt_pk_bf16_f32 v40, v30, v31
	v_cvt_pk_bf16_f32 v41, v32, v33
	global_store_dwordx2 v24, v[40:41], s[12:13]
	s_add_u32 s12, s12, 0x10000
	s_addc_u32 s13, s13, 0
	v_lshlrev_b32_e32 v34, 16, v142
	v_and_b32_e32 v35, 0xffff0000, v142
	v_lshlrev_b32_e32 v36, 16, v143
	v_and_b32_e32 v37, 0xffff0000, v143
	v_fma_f32 v30, v144, v30, v34
	v_fma_f32 v31, v145, v31, v35
	v_fma_f32 v32, v146, v32, v36
	v_fma_f32 v33, v147, v33, v37
	global_load_dwordx2 v[142:143], v24, s[10:11]
	global_load_dwordx4 v[144:147], v25, s[14:15]
	s_add_u32 s10, s10, 0x10000
	s_addc_u32 s11, s11, 0
	s_add_u32 s14, s14, 0x200
	s_addc_u32 s15, s15, 0
	s_waitcnt vmcnt(45)
	v_cvt_pk_bf16_f32 v38, v30, v31
	v_cvt_pk_bf16_f32 v39, v32, v33
	global_store_dwordx2 v24, v[38:39], s[12:13]
	s_add_u32 s12, s12, 0x10000
	s_addc_u32 s13, s13, 0
	v_lshlrev_b32_e32 v34, 16, v148
	v_and_b32_e32 v35, 0xffff0000, v148
	v_lshlrev_b32_e32 v36, 16, v149
	v_and_b32_e32 v37, 0xffff0000, v149
	v_fma_f32 v30, v150, v30, v34
	v_fma_f32 v31, v151, v31, v35
	v_fma_f32 v32, v152, v32, v36
	v_fma_f32 v33, v153, v33, v37
	global_load_dwordx2 v[148:149], v24, s[10:11]
	global_load_dwordx4 v[150:153], v25, s[14:15]
	s_add_u32 s10, s10, 0x10000
	s_addc_u32 s11, s11, 0
	s_add_u32 s14, s14, 0x200
	s_addc_u32 s15, s15, 0
	s_waitcnt vmcnt(45)
	v_cvt_pk_bf16_f32 v40, v30, v31
	v_cvt_pk_bf16_f32 v41, v32, v33
	global_store_dwordx2 v24, v[40:41], s[12:13]
	s_add_u32 s12, s12, 0x10000
	s_addc_u32 s13, s13, 0
	v_lshlrev_b32_e32 v34, 16, v154
	v_and_b32_e32 v35, 0xffff0000, v154
	v_lshlrev_b32_e32 v36, 16, v155
	v_and_b32_e32 v37, 0xffff0000, v155
	v_fma_f32 v30, v156, v30, v34
	v_fma_f32 v31, v157, v31, v35
	v_fma_f32 v32, v158, v32, v36
	v_fma_f32 v33, v159, v33, v37
	global_load_dwordx2 v[154:155], v24, s[10:11]
	global_load_dwordx4 v[156:159], v25, s[14:15]
	s_add_u32 s10, s10, 0x10000
	s_addc_u32 s11, s11, 0
	s_add_u32 s14, s14, 0x200
	s_addc_u32 s15, s15, 0
	s_waitcnt vmcnt(45)
	v_cvt_pk_bf16_f32 v38, v30, v31
	v_cvt_pk_bf16_f32 v39, v32, v33
	global_store_dwordx2 v24, v[38:39], s[12:13]
	s_add_u32 s12, s12, 0x10000
	s_addc_u32 s13, s13, 0
	v_lshlrev_b32_e32 v34, 16, v160
	v_and_b32_e32 v35, 0xffff0000, v160
	v_lshlrev_b32_e32 v36, 16, v161
	v_and_b32_e32 v37, 0xffff0000, v161
	v_fma_f32 v30, v162, v30, v34
	v_fma_f32 v31, v163, v31, v35
	v_fma_f32 v32, v164, v32, v36
	v_fma_f32 v33, v165, v33, v37
	global_load_dwordx2 v[160:161], v24, s[10:11]
	global_load_dwordx4 v[162:165], v25, s[14:15]
	s_add_u32 s10, s10, 0x10000
	s_addc_u32 s11, s11, 0
	s_add_u32 s14, s14, 0x200
	s_addc_u32 s15, s15, 0
	s_waitcnt vmcnt(45)
	v_cvt_pk_bf16_f32 v40, v30, v31
	v_cvt_pk_bf16_f32 v41, v32, v33
	global_store_dwordx2 v24, v[40:41], s[12:13]
	s_add_u32 s12, s12, 0x10000
	s_addc_u32 s13, s13, 0
	v_lshlrev_b32_e32 v34, 16, v166
	v_and_b32_e32 v35, 0xffff0000, v166
	v_lshlrev_b32_e32 v36, 16, v167
	v_and_b32_e32 v37, 0xffff0000, v167
	v_fma_f32 v30, v168, v30, v34
	v_fma_f32 v31, v169, v31, v35
	v_fma_f32 v32, v170, v32, v36
	v_fma_f32 v33, v171, v33, v37
	global_load_dwordx2 v[166:167], v24, s[10:11]
	global_load_dwordx4 v[168:171], v25, s[14:15]
	s_add_u32 s10, s10, 0x10000
	s_addc_u32 s11, s11, 0
	s_add_u32 s14, s14, 0x200
	s_addc_u32 s15, s15, 0
	s_waitcnt vmcnt(45)
	v_cvt_pk_bf16_f32 v38, v30, v31
	v_cvt_pk_bf16_f32 v39, v32, v33
	global_store_dwordx2 v24, v[38:39], s[12:13]
	s_add_u32 s12, s12, 0x10000
	s_addc_u32 s13, s13, 0
	v_lshlrev_b32_e32 v34, 16, v172
	v_and_b32_e32 v35, 0xffff0000, v172
	v_lshlrev_b32_e32 v36, 16, v173
	v_and_b32_e32 v37, 0xffff0000, v173
	v_fma_f32 v30, v174, v30, v34
	v_fma_f32 v31, v175, v31, v35
	v_fma_f32 v32, v176, v32, v36
	v_fma_f32 v33, v177, v33, v37
	global_load_dwordx2 v[172:173], v24, s[10:11]
	global_load_dwordx4 v[174:177], v25, s[14:15]
	s_add_u32 s10, s10, 0x10000
	s_addc_u32 s11, s11, 0
	s_add_u32 s14, s14, 0x200
	s_addc_u32 s15, s15, 0
	s_waitcnt vmcnt(45)
; __device__ __forceinline__ unsigned cvt_pk_bf16(float lo, float hi) { unsigned r; asm volatile("v_cvt_pk_bf16_f32 %0, %1, %2" : "=v"(r) : "v"(lo), "v"(hi)); return r; }
; __device__ __forceinline__ float bf_lo(unsigned w) { return __uint_as_float(w << 16); }
; __device__ __forceinline__ float bf_hi(unsigned w) { return __uint_as_float(w & 0xffff0000u); }
; __device__ __forceinline__ void gla_g2(const Params& P, unsigned char* lds) {
;     ...
;         for (int cb = 0; cb < 8; ++cb) {
;             u32x2 kv[8]; f32x4 d[8];
; #pragma unroll
;             for (int j = 0; j < 8; ++j) { const int it = bh * 64 + cb * 8 + j; kv[j] = *(const u32x2*)(KVT + ((size_t)it * 256 + dv) * 128 + dk4); d[j] = *(const f32x4*)(dec + (size_t)it * 128 + dk4); }
; #pragma unroll
;             for (int j = 0; j < 8; ++j) { const int it = bh * 64 + cb * 8 + j; u32x2 w; w.x = cvt_pk_bf16(S[0], S[1]); w.y = cvt_pk_bf16(S[2], S[3]);
;                 *(u32x2*)(KVT + ((size_t)it * 256 + dv) * 128 + dk4) = w;
;                 S[0] = d[j][0] * S[0] + bf_lo(kv[j].x); S[1] = d[j][1] * S[1] + bf_hi(kv[j].x); S[2] = d[j][2] * S[2] + bf_lo(kv[j].y); S[3] = d[j][3] * S[3] + bf_hi(kv[j].y); }
;         }
	v_cvt_pk_bf16_f32 v40, v30, v31
	v_cvt_pk_bf16_f32 v41, v32, v33
	global_store_dwordx2 v24, v[40:41], s[12:13]
	s_add_u32 s12, s12, 0x10000
	s_addc_u32 s13, s13, 0
	v_lshlrev_b32_e32 v34, 16, v178
	v_and_b32_e32 v35, 0xffff0000, v178
	v_lshlrev_b32_e32 v36, 16, v179
	v_and_b32_e32 v37, 0xffff0000, v179
	v_fma_f32 v30, v180, v30, v34
	v_fma_f32 v31, v181, v31, v35
	v_fma_f32 v32, v182, v32, v36
	v_fma_f32 v33, v183, v33, v37
	global_load_dwordx2 v[178:179], v24, s[10:11]
	global_load_dwordx4 v[180:183], v25, s[14:15]
	s_add_u32 s10, s10, 0x10000
	s_addc_u32 s11, s11, 0
	s_add_u32 s14, s14, 0x200
	s_addc_u32 s15, s15, 0
	s_waitcnt vmcnt(45)
	v_cvt_pk_bf16_f32 v38, v30, v31
	v_cvt_pk_bf16_f32 v39, v32, v33
	global_store_dwordx2 v24, v[38:39], s[12:13]
	s_add_u32 s12, s12, 0x10000
	s_addc_u32 s13, s13, 0
	v_lshlrev_b32_e32 v34, 16, v184
	v_and_b32_e32 v35, 0xffff0000, v184
	v_lshlrev_b32_e32 v36, 16, v185
	v_and_b32_e32 v37, 0xffff0000, v185
	v_fma_f32 v30, v186, v30, v34
	v_fma_f32 v31, v187, v31, v35
	v_fma_f32 v32, v188, v32, v36
	v_fma_f32 v33, v189, v33, v37
	global_load_dwordx2 v[184:185], v24, s[10:11]
	global_load_dwordx4 v[186:189], v25, s[14:15]
	s_add_u32 s10, s10, 0x10000
	s_addc_u32 s11, s11, 0
	s_add_u32 s14, s14, 0x200
	s_addc_u32 s15, s15, 0
	s_waitcnt vmcnt(45)
	v_cvt_pk_bf16_f32 v40, v30, v31
	v_cvt_pk_bf16_f32 v41, v32, v33
	global_store_dwordx2 v24, v[40:41], s[12:13]
	s_add_u32 s12, s12, 0x10000
	s_addc_u32 s13, s13, 0
	v_lshlrev_b32_e32 v34, 16, v190
	v_and_b32_e32 v35, 0xffff0000, v190
	v_lshlrev_b32_e32 v36, 16, v191
	v_and_b32_e32 v37, 0xffff0000, v191
	v_fma_f32 v30, v192, v30, v34
	v_fma_f32 v31, v193, v31, v35
	v_fma_f32 v32, v194, v32, v36
	v_fma_f32 v33, v195, v33, v37
	global_load_dwordx2 v[190:191], v24, s[10:11]
	global_load_dwordx4 v[192:195], v25, s[14:15]
	s_add_u32 s10, s10, 0x10000
	s_addc_u32 s11, s11, 0
	s_add_u32 s14, s14, 0x200
	s_addc_u32 s15, s15, 0
	s_waitcnt vmcnt(45)
	v_cvt_pk_bf16_f32 v38, v30, v31
	v_cvt_pk_bf16_f32 v39, v32, v33
	global_store_dwordx2 v24, v[38:39], s[12:13]
	s_add_u32 s12, s12, 0x10000
	s_addc_u32 s13, s13, 0
	v_lshlrev_b32_e32 v34, 16, v100
	v_and_b32_e32 v35, 0xffff0000, v100
	v_lshlrev_b32_e32 v36, 16, v101
	v_and_b32_e32 v37, 0xffff0000, v101
	v_fma_f32 v30, v102, v30, v34
	v_fma_f32 v31, v103, v31, v35
	v_fma_f32 v32, v104, v32, v36
	v_fma_f32 v33, v105, v33, v37
	s_waitcnt vmcnt(43)
	v_cvt_pk_bf16_f32 v40, v30, v31
	v_cvt_pk_bf16_f32 v41, v32, v33
	global_store_dwordx2 v24, v[40:41], s[12:13]
	s_add_u32 s12, s12, 0x10000
	s_addc_u32 s13, s13, 0
	v_lshlrev_b32_e32 v34, 16, v106
	v_and_b32_e32 v35, 0xffff0000, v106
	v_lshlrev_b32_e32 v36, 16, v107
	v_and_b32_e32 v37, 0xffff0000, v107
	v_fma_f32 v30, v108, v30, v34
	v_fma_f32 v31, v109, v31, v35
	v_fma_f32 v32, v110, v32, v36
	v_fma_f32 v33, v111, v33, v37
	s_waitcnt vmcnt(41)
	v_cvt_pk_bf16_f32 v38, v30, v31
	v_cvt_pk_bf16_f32 v39, v32, v33
	global_store_dwordx2 v24, v[38:39], s[12:13]
	s_add_u32 s12, s12, 0x10000
	s_addc_u32 s13, s13, 0
	v_lshlrev_b32_e32 v34, 16, v112
	v_and_b32_e32 v35, 0xffff0000, v112
	v_lshlrev_b32_e32 v36, 16, v113
	v_and_b32_e32 v37, 0xffff0000, v113
	v_fma_f32 v30, v114, v30, v34
	v_fma_f32 v31, v115, v31, v35
	v_fma_f32 v32, v116, v32, v36
	v_fma_f32 v33, v117, v33, v37
	s_waitcnt vmcnt(39)
	v_cvt_pk_bf16_f32 v40, v30, v31
	v_cvt_pk_bf16_f32 v41, v32, v33
	global_store_dwordx2 v24, v[40:41], s[12:13]
	s_add_u32 s12, s12, 0x10000
	s_addc_u32 s13, s13, 0
	v_lshlrev_b32_e32 v34, 16, v118
	v_and_b32_e32 v35, 0xffff0000, v118
	v_lshlrev_b32_e32 v36, 16, v119
	v_and_b32_e32 v37, 0xffff0000, v119
	v_fma_f32 v30, v120, v30, v34
	v_fma_f32 v31, v121, v31, v35
	v_fma_f32 v32, v122, v32, v36
	v_fma_f32 v33, v123, v33, v37
	s_waitcnt vmcnt(37)
	v_cvt_pk_bf16_f32 v38, v30, v31
	v_cvt_pk_bf16_f32 v39, v32, v33
	global_store_dwordx2 v24, v[38:39], s[12:13]
	s_add_u32 s12, s12, 0x10000
	s_addc_u32 s13, s13, 0
	v_lshlrev_b32_e32 v34, 16, v124
	v_and_b32_e32 v35, 0xffff0000, v124
	v_lshlrev_b32_e32 v36, 16, v125
	v_and_b32_e32 v37, 0xffff0000, v125
	v_fma_f32 v30, v126, v30, v34
	v_fma_f32 v31, v127, v31, v35
	v_fma_f32 v32, v128, v32, v36
	v_fma_f32 v33, v129, v33, v37
	s_waitcnt vmcnt(35)
	v_cvt_pk_bf16_f32 v40, v30, v31
	v_cvt_pk_bf16_f32 v41, v32, v33
	global_store_dwordx2 v24, v[40:41], s[12:13]
	s_add_u32 s12, s12, 0x10000
	s_addc_u32 s13, s13, 0
	v_lshlrev_b32_e32 v34, 16, v130
	v_and_b32_e32 v35, 0xffff0000, v130
	v_lshlrev_b32_e32 v36, 16, v131
	v_and_b32_e32 v37, 0xffff0000, v131
	v_fma_f32 v30, v132, v30, v34
	v_fma_f32 v31, v133, v31, v35
	v_fma_f32 v32, v134, v32, v36
	v_fma_f32 v33, v135, v33, v37
	s_waitcnt vmcnt(33)
	v_cvt_pk_bf16_f32 v38, v30, v31
	v_cvt_pk_bf16_f32 v39, v32, v33
	global_store_dwordx2 v24, v[38:39], s[12:13]
	s_add_u32 s12, s12, 0x10000
	s_addc_u32 s13, s13, 0
	v_lshlrev_b32_e32 v34, 16, v136
	v_and_b32_e32 v35, 0xffff0000, v136
	v_lshlrev_b32_e32 v36, 16, v137
	v_and_b32_e32 v37, 0xffff0000, v137
	v_fma_f32 v30, v138, v30, v34
	v_fma_f32 v31, v139, v31, v35
	v_fma_f32 v32, v140, v32, v36
	v_fma_f32 v33, v141, v33, v37
	s_waitcnt vmcnt(31)
	v_cvt_pk_bf16_f32 v40, v30, v31
	v_cvt_pk_bf16_f32 v41, v32, v33
	global_store_dwordx2 v24, v[40:41], s[12:13]
	s_add_u32 s12, s12, 0x10000
	s_addc_u32 s13, s13, 0
	v_lshlrev_b32_e32 v34, 16, v142
	v_and_b32_e32 v35, 0xffff0000, v142
	v_lshlrev_b32_e32 v36, 16, v143
	v_and_b32_e32 v37, 0xffff0000, v143
	v_fma_f32 v30, v144, v30, v34
	v_fma_f32 v31, v145, v31, v35
	v_fma_f32 v32, v146, v32, v36
	v_fma_f32 v33, v147, v33, v37
	s_waitcnt vmcnt(29)
; __device__ __forceinline__ unsigned cvt_pk_bf16(float lo, float hi) { unsigned r; asm volatile("v_cvt_pk_bf16_f32 %0, %1, %2" : "=v"(r) : "v"(lo), "v"(hi)); return r; }
; __device__ __forceinline__ float bf_lo(unsigned w) { return __uint_as_float(w << 16); }
; __device__ __forceinline__ float bf_hi(unsigned w) { return __uint_as_float(w & 0xffff0000u); }
; __device__ __forceinline__ void gla_g2(const Params& P, unsigned char* lds) {
;     ...
;         for (int cb = 0; cb < 8; ++cb) {
;             u32x2 kv[8]; f32x4 d[8];
; #pragma unroll
;             for (int j = 0; j < 8; ++j) { const int it = bh * 64 + cb * 8 + j; kv[j] = *(const u32x2*)(KVT + ((size_t)it * 256 + dv) * 128 + dk4); d[j] = *(const f32x4*)(dec + (size_t)it * 128 + dk4); }
; #pragma unroll
;             for (int j = 0; j < 8; ++j) { const int it = bh * 64 + cb * 8 + j; u32x2 w; w.x = cvt_pk_bf16(S[0], S[1]); w.y = cvt_pk_bf16(S[2], S[3]);
;                 *(u32x2*)(KVT + ((size_t)it * 256 + dv) * 128 + dk4) = w;
;                 S[0] = d[j][0] * S[0] + bf_lo(kv[j].x); S[1] = d[j][1] * S[1] + bf_hi(kv[j].x); S[2] = d[j][2] * S[2] + bf_lo(kv[j].y); S[3] = d[j][3] * S[3] + bf_hi(kv[j].y); }
;         }
;         __syncthreads();
; #pragma unroll
;         for (int i = 0; i < 4; ++i) tile[(dk4 + i) * 17 + dvl] = S[i];
;         __syncthreads();
	v_cvt_pk_bf16_f32 v38, v30, v31
	v_cvt_pk_bf16_f32 v39, v32, v33
	global_store_dwordx2 v24, v[38:39], s[12:13]
	s_add_u32 s12, s12, 0x10000
	s_addc_u32 s13, s13, 0
	v_lshlrev_b32_e32 v34, 16, v148
	v_and_b32_e32 v35, 0xffff0000, v148
	v_lshlrev_b32_e32 v36, 16, v149
	v_and_b32_e32 v37, 0xffff0000, v149
	v_fma_f32 v30, v150, v30, v34
	v_fma_f32 v31, v151, v31, v35
	v_fma_f32 v32, v152, v32, v36
	v_fma_f32 v33, v153, v33, v37
	s_waitcnt vmcnt(27)
	v_cvt_pk_bf16_f32 v40, v30, v31
	v_cvt_pk_bf16_f32 v41, v32, v33
	global_store_dwordx2 v24, v[40:41], s[12:13]
	s_add_u32 s12, s12, 0x10000
	s_addc_u32 s13, s13, 0
	v_lshlrev_b32_e32 v34, 16, v154
	v_and_b32_e32 v35, 0xffff0000, v154
	v_lshlrev_b32_e32 v36, 16, v155
	v_and_b32_e32 v37, 0xffff0000, v155
	v_fma_f32 v30, v156, v30, v34
	v_fma_f32 v31, v157, v31, v35
	v_fma_f32 v32, v158, v32, v36
	v_fma_f32 v33, v159, v33, v37
	s_waitcnt vmcnt(25)
	v_cvt_pk_bf16_f32 v38, v30, v31
	v_cvt_pk_bf16_f32 v39, v32, v33
	global_store_dwordx2 v24, v[38:39], s[12:13]
	s_add_u32 s12, s12, 0x10000
	s_addc_u32 s13, s13, 0
	v_lshlrev_b32_e32 v34, 16, v160
	v_and_b32_e32 v35, 0xffff0000, v160
	v_lshlrev_b32_e32 v36, 16, v161
	v_and_b32_e32 v37, 0xffff0000, v161
	v_fma_f32 v30, v162, v30, v34
	v_fma_f32 v31, v163, v31, v35
	v_fma_f32 v32, v164, v32, v36
	v_fma_f32 v33, v165, v33, v37
	s_waitcnt vmcnt(23)
	v_cvt_pk_bf16_f32 v40, v30, v31
	v_cvt_pk_bf16_f32 v41, v32, v33
	global_store_dwordx2 v24, v[40:41], s[12:13]
	s_add_u32 s12, s12, 0x10000
	s_addc_u32 s13, s13, 0
	v_lshlrev_b32_e32 v34, 16, v166
	v_and_b32_e32 v35, 0xffff0000, v166
	v_lshlrev_b32_e32 v36, 16, v167
	v_and_b32_e32 v37, 0xffff0000, v167
	v_fma_f32 v30, v168, v30, v34
	v_fma_f32 v31, v169, v31, v35
	v_fma_f32 v32, v170, v32, v36
	v_fma_f32 v33, v171, v33, v37
	s_waitcnt vmcnt(21)
	v_cvt_pk_bf16_f32 v38, v30, v31
	v_cvt_pk_bf16_f32 v39, v32, v33
	global_store_dwordx2 v24, v[38:39], s[12:13]
	s_add_u32 s12, s12, 0x10000
	s_addc_u32 s13, s13, 0
	v_lshlrev_b32_e32 v34, 16, v172
	v_and_b32_e32 v35, 0xffff0000, v172
	v_lshlrev_b32_e32 v36, 16, v173
	v_and_b32_e32 v37, 0xffff0000, v173
	v_fma_f32 v30, v174, v30, v34
	v_fma_f32 v31, v175, v31, v35
	v_fma_f32 v32, v176, v32, v36
	v_fma_f32 v33, v177, v33, v37
	s_waitcnt vmcnt(19)
	v_cvt_pk_bf16_f32 v40, v30, v31
	v_cvt_pk_bf16_f32 v41, v32, v33
	global_store_dwordx2 v24, v[40:41], s[12:13]
	s_add_u32 s12, s12, 0x10000
	s_addc_u32 s13, s13, 0
	v_lshlrev_b32_e32 v34, 16, v178
	v_and_b32_e32 v35, 0xffff0000, v178
	v_lshlrev_b32_e32 v36, 16, v179
	v_and_b32_e32 v37, 0xffff0000, v179
	v_fma_f32 v30, v180, v30, v34
	v_fma_f32 v31, v181, v31, v35
	v_fma_f32 v32, v182, v32, v36
	v_fma_f32 v33, v183, v33, v37
	s_waitcnt vmcnt(17)
	v_cvt_pk_bf16_f32 v38, v30, v31
	v_cvt_pk_bf16_f32 v39, v32, v33
	global_store_dwordx2 v24, v[38:39], s[12:13]
	s_add_u32 s12, s12, 0x10000
	s_addc_u32 s13, s13, 0
	v_lshlrev_b32_e32 v34, 16, v184
	v_and_b32_e32 v35, 0xffff0000, v184
	v_lshlrev_b32_e32 v36, 16, v185
	v_and_b32_e32 v37, 0xffff0000, v185
	v_fma_f32 v30, v186, v30, v34
	v_fma_f32 v31, v187, v31, v35
	v_fma_f32 v32, v188, v32, v36
	v_fma_f32 v33, v189, v33, v37
	s_waitcnt vmcnt(15)
	v_cvt_pk_bf16_f32 v40, v30, v31
	v_cvt_pk_bf16_f32 v41, v32, v33
	global_store_dwordx2 v24, v[40:41], s[12:13]
	s_add_u32 s12, s12, 0x10000
	s_addc_u32 s13, s13, 0
	v_lshlrev_b32_e32 v34, 16, v190
	v_and_b32_e32 v35, 0xffff0000, v190
	v_lshlrev_b32_e32 v36, 16, v191
	v_and_b32_e32 v37, 0xffff0000, v191
	v_fma_f32 v30, v192, v30, v34
	v_fma_f32 v31, v193, v31, v35
	v_fma_f32 v32, v194, v32, v36
	v_fma_f32 v33, v195, v33, v37
	s_barrier
	ds_write2_b32 v26, v30, v31 offset1:17
	ds_write2_b32 v26, v32, v33 offset0:34 offset1:51
	s_waitcnt lgkmcnt(0)
	s_barrier
; __device__ __forceinline__ unsigned cvt_pk_bf16(float lo, float hi) { unsigned r; asm volatile("v_cvt_pk_bf16_f32 %0, %1, %2" : "=v"(r) : "v"(lo), "v"(hi)); return r; }
; __device__ __forceinline__ float bf_lo(unsigned w) { return __uint_as_float(w << 16); }
; __device__ __forceinline__ float bf_hi(unsigned w) { return __uint_as_float(w & 0xffff0000u); }
; __device__ __forceinline__ void gla_g2(const Params& P, unsigned char* lds) {
;     ...
;         __syncthreads();
; #pragma unroll
;         for (int i = 0; i < 4; ++i) tile[(dk4 + i) * 17 + dvl] = S[i];
;         __syncthreads();
;         { f32x4 o; o[0] = tile[odk * 17 + odv4]; o[1] = tile[odk * 17 + odv4 + 1]; o[2] = tile[odk * 17 + odv4 + 2]; o[3] = tile[odk * 17 + odv4 + 3];
;             *(f32x4*)(P.out + OUT_GSP + ((size_t)bh * 128 + odk) * 256 + dvb * 16 + odv4) = o; }
;     }
;     for (int u = blockIdx.x; u < 1024; u += gridDim.x) {
;         const int j = u >> 4, dvb = u & 15, it = 1024 + j, dv = dvb * 16 + dvl;
;         __syncthreads();
;         { const f32x4 v = *(const f32x4*)(P.in[3] + ((size_t)j * 128 + odk) * 256 + dvb * 16 + odv4);
; #pragma unroll
;             for (int i = 0; i < 4; ++i) tile[odk * 17 + odv4 + i] = v[i]; }
;         __syncthreads();
;         f32x4 s, f;
; #pragma unroll
;         for (int i = 0; i < 4; ++i) s[i] = tile[(dk4 + i) * 17 + dvl];
;         const u32x2 kv = *(const u32x2*)(KVT + ((size_t)it * 256 + dv) * 128 + dk4); const f32x4 d = *(const f32x4*)(dec + (size_t)it * 128 + dk4);
;         { u32x2 w; w.x = cvt_pk_bf16(s[0], s[1]); w.y = cvt_pk_bf16(s[2], s[3]); *(u32x2*)(KVT + ((size_t)it * 256 + dv) * 128 + dk4) = w; }
;         f[0] = d[0] * s[0] + bf_lo(kv.x); f[1] = d[1] * s[1] + bf_hi(kv.x); f[2] = d[2] * s[2] + bf_lo(kv.y); f[3] = d[3] * s[3] + bf_hi(kv.y);
;         __syncthreads();
; #pragma unroll
;         for (int i = 0; i < 4; ++i) tile[(dk4 + i) * 17 + dvl] = f[i];
;         __syncthreads();
;         { f32x4 o; o[0] = tile[odk * 17 + odv4]; o[1] = tile[odk * 17 + odv4 + 1]; o[2] = tile[odk * 17 + odv4 + 2]; o[3] = tile[odk * 17 + odv4 + 3];
;             *(f32x4*)(P.out + OUT_GSS + ((size_t)j * 128 + odk) * 256 + dvb * 16 + odv4) = o; }
;     }
	ds_read2_b32 v[0:1], v27 offset1:1
	ds_read2_b32 v[2:3], v27 offset0:2 offset1:3
	s_waitcnt lgkmcnt(0)
	global_store_dwordx4 v28, v[0:3], s[16:17]
	v_add_u32_e32 v48, 0x2400, v27
	v_add_u32_e32 v52, 0x2400, v26
	ds_write2_b32 v48, v60, v61 offset1:1
	ds_write2_b32 v48, v62, v63 offset0:2 offset1:3
	v_add_u32_e32 v49, 0x4800, v27
	v_add_u32_e32 v53, 0x4800, v26
	ds_write2_b32 v49, v70, v71 offset1:1
	ds_write2_b32 v49, v72, v73 offset0:2 offset1:3
	v_add_u32_e32 v50, 0x6c00, v27
	v_add_u32_e32 v54, 0x6c00, v26
	ds_write2_b32 v50, v80, v81 offset1:1
	ds_write2_b32 v50, v82, v83 offset0:2 offset1:3
	v_add_u32_e32 v51, 0x9000, v27
	v_add_u32_e32 v55, 0x9000, v26
	ds_write2_b32 v51, v90, v91 offset1:1
	ds_write2_b32 v51, v92, v93 offset0:2 offset1:3
	s_waitcnt lgkmcnt(0)
	s_barrier
	ds_read2_b32 v[60:61], v52 offset1:17
	ds_read2_b32 v[62:63], v52 offset0:34 offset1:51
	ds_read2_b32 v[70:71], v53 offset1:17
	ds_read2_b32 v[72:73], v53 offset0:34 offset1:51
	ds_read2_b32 v[80:81], v54 offset1:17
	ds_read2_b32 v[82:83], v54 offset0:34 offset1:51
	ds_read2_b32 v[90:91], v55 offset1:17
	ds_read2_b32 v[92:93], v55 offset0:34 offset1:51
	s_waitcnt lgkmcnt(0)
	v_cvt_pk_bf16_f32 v38, v60, v61
	v_cvt_pk_bf16_f32 v39, v62, v63
	global_store_dwordx2 v24, v[38:39], s[18:19]
	v_lshlrev_b32_e32 v34, 16, v64
	v_and_b32_e32 v35, 0xffff0000, v64
	v_lshlrev_b32_e32 v36, 16, v65
	v_and_b32_e32 v37, 0xffff0000, v65
	v_fma_f32 v60, v66, v60, v34
	v_fma_f32 v61, v67, v61, v35
	v_fma_f32 v62, v68, v62, v36
	v_fma_f32 v63, v69, v63, v37
	ds_write2_b32 v52, v60, v61 offset1:17
	ds_write2_b32 v52, v62, v63 offset0:34 offset1:51
	v_cvt_pk_bf16_f32 v40, v70, v71
	v_cvt_pk_bf16_f32 v41, v72, v73
	v_add_u32_e32 v45, 0x100000, v24
	global_store_dwordx2 v45, v[40:41], s[18:19]
	v_lshlrev_b32_e32 v34, 16, v74
	v_and_b32_e32 v35, 0xffff0000, v74
	v_lshlrev_b32_e32 v36, 16, v75
	v_and_b32_e32 v37, 0xffff0000, v75
	v_fma_f32 v70, v76, v70, v34
	v_fma_f32 v71, v77, v71, v35
	v_fma_f32 v72, v78, v72, v36
	v_fma_f32 v73, v79, v73, v37
	ds_write2_b32 v53, v70, v71 offset1:17
	ds_write2_b32 v53, v72, v73 offset0:34 offset1:51
	v_cvt_pk_bf16_f32 v38, v80, v81
	v_cvt_pk_bf16_f32 v39, v82, v83
	v_add_u32_e32 v45, 0x200000, v24
	global_store_dwordx2 v45, v[38:39], s[18:19]
	v_lshlrev_b32_e32 v34, 16, v84
	v_and_b32_e32 v35, 0xffff0000, v84
	v_lshlrev_b32_e32 v36, 16, v85
	v_and_b32_e32 v37, 0xffff0000, v85
	v_fma_f32 v80, v86, v80, v34
	v_fma_f32 v81, v87, v81, v35
	v_fma_f32 v82, v88, v82, v36
	v_fma_f32 v83, v89, v83, v37
	ds_write2_b32 v54, v80, v81 offset1:17
	ds_write2_b32 v54, v82, v83 offset0:34 offset1:51
	v_cvt_pk_bf16_f32 v40, v90, v91
	v_cvt_pk_bf16_f32 v41, v92, v93
	v_add_u32_e32 v45, 0x300000, v24
	global_store_dwordx2 v45, v[40:41], s[18:19]
	v_lshlrev_b32_e32 v34, 16, v94
	v_and_b32_e32 v35, 0xffff0000, v94
	v_lshlrev_b32_e32 v36, 16, v95
	v_and_b32_e32 v37, 0xffff0000, v95
	v_fma_f32 v90, v96, v90, v34
	v_fma_f32 v91, v97, v91, v35
	v_fma_f32 v92, v98, v92, v36
	v_fma_f32 v93, v99, v93, v37
	ds_write2_b32 v55, v90, v91 offset1:17
	ds_write2_b32 v55, v92, v93 offset0:34 offset1:51
	s_waitcnt lgkmcnt(0)
	s_barrier
	ds_read2_b32 v[60:61], v48 offset1:1
	ds_read2_b32 v[62:63], v48 offset0:2 offset1:3
	ds_read2_b32 v[70:71], v49 offset1:1
	ds_read2_b32 v[72:73], v49 offset0:2 offset1:3
	ds_read2_b32 v[80:81], v50 offset1:1
	ds_read2_b32 v[82:83], v50 offset0:2 offset1:3
	ds_read2_b32 v[90:91], v51 offset1:1
	ds_read2_b32 v[92:93], v51 offset0:2 offset1:3
	s_waitcnt lgkmcnt(0)
	global_store_dwordx4 v28, v[60:63], s[100:101]
	v_add_u32_e32 v44, 0x200000, v28
	global_store_dwordx4 v44, v[70:73], s[100:101]
	v_add_u32_e32 v44, 0x400000, v28
	global_store_dwordx4 v44, v[80:83], s[100:101]
	v_add_u32_e32 v44, 0x600000, v28
	global_store_dwordx4 v44, v[90:93], s[100:101]
